# hand-written FFN2 weight transposes (8x dwordx4 in flight, no 64-bit mads) on scan WGs
# baseline (speedup 1.0000x reference)
; #define LAS __attribute__((address_space(3)))
; __device__ __forceinline__ unsigned pk2(float lo, float hi) { f32x2 v = {lo, hi}; bf16x2_t b = __builtin_convertvector(v, bf16x2_t); return __builtin_bit_cast(unsigned, b); }
;     __device__ __forceinline__ const float* in(int i) const { return (const float*)ptr(i); }
;     __device__ __forceinline__ unsigned char* ws() const { return (unsigned char*)ptr(37); }
; #define ws (p.ws())
; __device__ __forceinline__ void transpose_item(const float* W, int K, int N, bf16_t* WT, int k0, int n0, int drow0, LAS float* scr, int lane) {
; #pragma unroll 8
;     for (int i = 0; i < 32; ++i) { const int kk = 2 * i + (lane >> 5); scr[kk * 33 + (lane & 31)] = W[(size_t)(k0 + kk) * N + n0 + (lane & 31)]; }
;     asm volatile("s_waitcnt lgkmcnt(0)" ::: "memory");
;     const int c = lane & 7;
; #pragma unroll
;     for (int j = 0; j < 4; ++j) { const int n = (lane >> 3) + 8 * j; const LAS float* s = scr + (8 * c) * 33 + n;
;         u32x4 o; o.x = pk2(s[0 * 33], s[1 * 33]); o.y = pk2(s[2 * 33], s[3 * 33]); o.z = pk2(s[4 * 33], s[5 * 33]); o.w = pk2(s[6 * 33], s[7 * 33]);
;         *(u32x4*)(WT + (size_t)(drow0 + n) * K + k0 + 8 * c) = o; }
;     asm volatile("s_waitcnt lgkmcnt(0)" ::: "memory");
; }
; __device__ __forceinline__ void ffn2_weights(const Ctx& p, LAS unsigned char* lds) {
;     ...
;     constexpr int I7 = 16 * 176, I8 = 44 * 32;
;     __syncthreads();
;     for (int it = ((int)blockIdx.x - 128) * 8 + wave; it < I7 + I8; it += 128 * 8) {
;         int r = it;
;         if (r < I7) { const int kb = r / 176, nb = r % 176; transpose_item(p.in(33), DM, NFF, (bf16_t*)(ws + WS_W3T), 64 * kb, 32 * nb, map_w1(32 * nb), scr, lane); continue; } r -= I7;
;         { const int kb = r / 32, nb = r % 32; transpose_item(p.in(34), DFF, DM, (bf16_t*)(ws + WS_W4T), 64 * kb, 32 * nb, 32 * nb, scr, lane); }
;     }
.Lscan_ffn2w:
	s_waitcnt vmcnt(0) lgkmcnt(0)
	s_barrier
	v_mov_b32_e32 v0, 0x23508
	v_mov_b32_e32 v1, 0x23510
	v_mov_b32_e32 v2, 0x23528
	ds_read_b64 v[4:5], v0
	ds_read_b64 v[6:7], v1
	ds_read_b64 v[8:9], v2
	v_readfirstlane_b32 s2, v180
	s_waitcnt lgkmcnt(0)
	v_readfirstlane_b32 s8, v4
	v_readfirstlane_b32 s9, v5
	v_readfirstlane_b32 s10, v6
	v_readfirstlane_b32 s11, v7
	v_readfirstlane_b32 s12, v8
	v_readfirstlane_b32 s13, v9
	s_nop 4
	s_lshr_b32 s27, s2, 6
	s_lshl_b32 s26, s28, 3
	s_add_i32 s26, s26, s27
	s_lshl_b32 s3, s27, 14
	v_and_b32_e32 v0, 63, v180
	v_lshrrev_b32_e32 v1, 3, v0
	v_and_b32_e32 v2, 7, v0
	v_mul_u32_u24_e32 v14, 0x84, v1
	v_lshl_add_u32 v14, v2, 4, v14
	v_add_u32_e32 v14, s3, v14
	v_mul_u32_u24_e32 v15, 0x420, v2
	v_lshl_add_u32 v15, v1, 2, v15
	v_add_u32_e32 v15, s3, v15
	v_mul_u32_u24_e32 v13, 0x5800, v1
	v_lshl_add_u32 v13, v2, 4, v13
	v_lshlrev_b32_e32 v4, 11, v1
	v_lshl_add_u32 v4, v2, 4, v4
	v_add_u32_e32 v5, 0x4000, v4
	v_add_u32_e32 v6, 0x8000, v4
	v_add_u32_e32 v7, 0xc000, v4
	s_add_u32 s18, s12, 0x1f00000
	s_addc_u32 s19, s13, 0
.Lffn2w_w3:
	s_cmpk_gt_u32 s26, 0xaff
	s_cbranch_scc1 .Lffn2w_w3_done
	s_mul_hi_u32 s4, s26, 0x1745d18
	s_mul_i32 s5, s4, 0xb0
	s_sub_u32 s5, s26, s5
	s_mul_i32 s6, s4, 0x160000
	s_lshl_b32 s7, s5, 7
	s_add_u32 s6, s6, s7
	s_add_u32 s14, s8, s6
	s_addc_u32 s15, s9, 0
	s_cmpk_lt_u32 s5, 0x58
	s_cselect_b32 s20, 0, 0x80
	s_cselect_b32 s21, 0, 0x58
	s_sub_u32 s5, s5, s21
	s_lshr_b32 s21, s5, 2
	s_lshl_b32 s21, s21, 8
	s_and_b32 s5, s5, 3
	s_lshl_b32 s5, s5, 5
	s_add_u32 s21, s21, s5
	s_add_u32 s21, s21, s20
	s_lshl_b32 s21, s21, 11
	s_lshl_b32 s4, s4, 7
	s_add_u32 s21, s21, s4
	s_add_u32 s16, s18, s21
	s_addc_u32 s17, s19, 0
	global_load_dwordx4 v[16:19], v13, s[14:15]
	v_add_u32_e32 v12, 0x2c000, v13
	global_load_dwordx4 v[20:23], v12, s[14:15]
	v_add_u32_e32 v12, 0x2c000, v12
	global_load_dwordx4 v[24:27], v12, s[14:15]
	v_add_u32_e32 v12, 0x2c000, v12
	global_load_dwordx4 v[28:31], v12, s[14:15]
	v_add_u32_e32 v12, 0x2c000, v12
	global_load_dwordx4 v[32:35], v12, s[14:15]
	v_add_u32_e32 v12, 0x2c000, v12
	global_load_dwordx4 v[36:39], v12, s[14:15]
	v_add_u32_e32 v12, 0x2c000, v12
	global_load_dwordx4 v[40:43], v12, s[14:15]
	v_add_u32_e32 v12, 0x2c000, v12
	global_load_dwordx4 v[44:47], v12, s[14:15]
	s_waitcnt vmcnt(7)
	ds_write_b32 v14, v16 offset:0
	ds_write_b32 v14, v17 offset:4
	ds_write_b32 v14, v18 offset:8
	ds_write_b32 v14, v19 offset:12
	s_waitcnt vmcnt(6)
	ds_write_b32 v14, v20 offset:1056
	ds_write_b32 v14, v21 offset:1060
	ds_write_b32 v14, v22 offset:1064
	ds_write_b32 v14, v23 offset:1068
	s_waitcnt vmcnt(5)
	ds_write_b32 v14, v24 offset:2112
	ds_write_b32 v14, v25 offset:2116
	ds_write_b32 v14, v26 offset:2120
	ds_write_b32 v14, v27 offset:2124
	s_waitcnt vmcnt(4)
	ds_write_b32 v14, v28 offset:3168
	ds_write_b32 v14, v29 offset:3172
	ds_write_b32 v14, v30 offset:3176
	ds_write_b32 v14, v31 offset:3180
	s_waitcnt vmcnt(3)
	ds_write_b32 v14, v32 offset:4224
	ds_write_b32 v14, v33 offset:4228
	ds_write_b32 v14, v34 offset:4232
	ds_write_b32 v14, v35 offset:4236
	s_waitcnt vmcnt(2)
	ds_write_b32 v14, v36 offset:5280
	ds_write_b32 v14, v37 offset:5284
	ds_write_b32 v14, v38 offset:5288
	ds_write_b32 v14, v39 offset:5292
	s_waitcnt vmcnt(1)
	ds_write_b32 v14, v40 offset:6336
	ds_write_b32 v14, v41 offset:6340
	ds_write_b32 v14, v42 offset:6344
	ds_write_b32 v14, v43 offset:6348
	s_waitcnt vmcnt(0)
	ds_write_b32 v14, v44 offset:7392
	ds_write_b32 v14, v45 offset:7396
	ds_write_b32 v14, v46 offset:7400
	ds_write_b32 v14, v47 offset:7404
	s_waitcnt lgkmcnt(0)
	ds_read2_b32 v[80:81], v15 offset0:0 offset1:33
	ds_read2_b32 v[82:83], v15 offset0:66 offset1:99
	ds_read2_b32 v[84:85], v15 offset0:132 offset1:165
	ds_read2_b32 v[86:87], v15 offset0:198 offset1:231
	ds_read2_b32 v[88:89], v15 offset0:8 offset1:41
	ds_read2_b32 v[90:91], v15 offset0:74 offset1:107
	ds_read2_b32 v[92:93], v15 offset0:140 offset1:173
	ds_read2_b32 v[94:95], v15 offset0:206 offset1:239
	s_waitcnt lgkmcnt(4)
	v_cvt_pk_bf16_f32 v112, v80, v81
	v_cvt_pk_bf16_f32 v113, v82, v83
	v_cvt_pk_bf16_f32 v114, v84, v85
	v_cvt_pk_bf16_f32 v115, v86, v87
	global_store_dwordx4 v4, v[112:115], s[16:17]
	s_waitcnt lgkmcnt(0)
	v_cvt_pk_bf16_f32 v116, v88, v89
	v_cvt_pk_bf16_f32 v117, v90, v91
	v_cvt_pk_bf16_f32 v118, v92, v93
	v_cvt_pk_bf16_f32 v119, v94, v95
	global_store_dwordx4 v5, v[116:119], s[16:17]
	ds_read2_b32 v[96:97], v15 offset0:16 offset1:49
	ds_read2_b32 v[98:99], v15 offset0:82 offset1:115
	ds_read2_b32 v[100:101], v15 offset0:148 offset1:181
	ds_read2_b32 v[102:103], v15 offset0:214 offset1:247
	ds_read2_b32 v[104:105], v15 offset0:24 offset1:57
	ds_read2_b32 v[106:107], v15 offset0:90 offset1:123
	ds_read2_b32 v[108:109], v15 offset0:156 offset1:189
	ds_read2_b32 v[110:111], v15 offset0:222 offset1:255
	s_waitcnt lgkmcnt(4)
	v_cvt_pk_bf16_f32 v120, v96, v97
	v_cvt_pk_bf16_f32 v121, v98, v99
	v_cvt_pk_bf16_f32 v122, v100, v101
	v_cvt_pk_bf16_f32 v123, v102, v103
	global_store_dwordx4 v6, v[120:123], s[16:17]
	s_waitcnt lgkmcnt(0)
	v_cvt_pk_bf16_f32 v124, v104, v105
	v_cvt_pk_bf16_f32 v125, v106, v107
	v_cvt_pk_bf16_f32 v126, v108, v109
	v_cvt_pk_bf16_f32 v127, v110, v111
	global_store_dwordx4 v7, v[124:127], s[16:17]
	s_addk_i32 s26, 0x400
	s_branch .Lffn2w_w3
; #define LAS __attribute__((address_space(3)))
; __device__ __forceinline__ unsigned pk2(float lo, float hi) { f32x2 v = {lo, hi}; bf16x2_t b = __builtin_convertvector(v, bf16x2_t); return __builtin_bit_cast(unsigned, b); }
;     __device__ __forceinline__ const float* in(int i) const { return (const float*)ptr(i); }
;     __device__ __forceinline__ unsigned char* ws() const { return (unsigned char*)ptr(37); }
; #define ws (p.ws())
; __device__ __forceinline__ void transpose_item(const float* W, int K, int N, bf16_t* WT, int k0, int n0, int drow0, LAS float* scr, int lane) {
; #pragma unroll 8
;     for (int i = 0; i < 32; ++i) { const int kk = 2 * i + (lane >> 5); scr[kk * 33 + (lane & 31)] = W[(size_t)(k0 + kk) * N + n0 + (lane & 31)]; }
;     asm volatile("s_waitcnt lgkmcnt(0)" ::: "memory");
;     const int c = lane & 7;
; #pragma unroll
;     for (int j = 0; j < 4; ++j) { const int n = (lane >> 3) + 8 * j; const LAS float* s = scr + (8 * c) * 33 + n;
;         u32x4 o; o.x = pk2(s[0 * 33], s[1 * 33]); o.y = pk2(s[2 * 33], s[3 * 33]); o.z = pk2(s[4 * 33], s[5 * 33]); o.w = pk2(s[6 * 33], s[7 * 33]);
;         *(u32x4*)(WT + (size_t)(drow0 + n) * K + k0 + 8 * c) = o; }
;     asm volatile("s_waitcnt lgkmcnt(0)" ::: "memory");
; }
; __device__ __forceinline__ void ffn2_weights(const Ctx& p, LAS unsigned char* lds) {
;     ...
;         { const int kb = r / 32, nb = r % 32; transpose_item(p.in(34), DFF, DM, (bf16_t*)(ws + WS_W4T), 64 * kb, 32 * nb, 32 * nb, scr, lane); }
.Lffn2w_w3_done:
	s_sub_u32 s26, s26, 0xb00
	v_lshlrev_b32_e32 v13, 12, v1
	v_lshl_add_u32 v13, v2, 4, v13
	v_mul_u32_u24_e32 v4, 0x1600, v1
	v_lshl_add_u32 v4, v2, 4, v4
	v_add_u32_e32 v5, 0xb000, v4
	v_add_u32_e32 v6, 0x16000, v4
	v_add_u32_e32 v7, 0x21000, v4
	s_add_u32 s18, s12, 0x2a00000
	s_addc_u32 s19, s13, 0
.Lffn2w_w4:
	s_cmpk_gt_u32 s26, 0x57f
	s_cbranch_scc1 .Lffn2w_done
	s_lshr_b32 s4, s26, 5
	s_and_b32 s5, s26, 31
	s_lshl_b32 s6, s4, 18
	s_lshl_b32 s7, s5, 7
	s_add_u32 s6, s6, s7
	s_add_u32 s14, s10, s6
	s_addc_u32 s15, s11, 0
	s_mul_i32 s21, s5, 0x2c000
	s_lshl_b32 s4, s4, 7
	s_add_u32 s21, s21, s4
	s_add_u32 s16, s18, s21
	s_addc_u32 s17, s19, 0
	global_load_dwordx4 v[16:19], v13, s[14:15]
	v_add_u32_e32 v12, 0x8000, v13
	global_load_dwordx4 v[20:23], v12, s[14:15]
	v_add_u32_e32 v12, 0x8000, v12
	global_load_dwordx4 v[24:27], v12, s[14:15]
	v_add_u32_e32 v12, 0x8000, v12
	global_load_dwordx4 v[28:31], v12, s[14:15]
	v_add_u32_e32 v12, 0x8000, v12
	global_load_dwordx4 v[32:35], v12, s[14:15]
	v_add_u32_e32 v12, 0x8000, v12
	global_load_dwordx4 v[36:39], v12, s[14:15]
	v_add_u32_e32 v12, 0x8000, v12
	global_load_dwordx4 v[40:43], v12, s[14:15]
	v_add_u32_e32 v12, 0x8000, v12
	global_load_dwordx4 v[44:47], v12, s[14:15]
	s_waitcnt vmcnt(7)
	ds_write_b32 v14, v16 offset:0
	ds_write_b32 v14, v17 offset:4
	ds_write_b32 v14, v18 offset:8
	ds_write_b32 v14, v19 offset:12
	s_waitcnt vmcnt(6)
	ds_write_b32 v14, v20 offset:1056
	ds_write_b32 v14, v21 offset:1060
	ds_write_b32 v14, v22 offset:1064
	ds_write_b32 v14, v23 offset:1068
	s_waitcnt vmcnt(5)
	ds_write_b32 v14, v24 offset:2112
	ds_write_b32 v14, v25 offset:2116
	ds_write_b32 v14, v26 offset:2120
	ds_write_b32 v14, v27 offset:2124
	s_waitcnt vmcnt(4)
	ds_write_b32 v14, v28 offset:3168
	ds_write_b32 v14, v29 offset:3172
	ds_write_b32 v14, v30 offset:3176
	ds_write_b32 v14, v31 offset:3180
	s_waitcnt vmcnt(3)
	ds_write_b32 v14, v32 offset:4224
	ds_write_b32 v14, v33 offset:4228
	ds_write_b32 v14, v34 offset:4232
	ds_write_b32 v14, v35 offset:4236
	s_waitcnt vmcnt(2)
	ds_write_b32 v14, v36 offset:5280
	ds_write_b32 v14, v37 offset:5284
	ds_write_b32 v14, v38 offset:5288
	ds_write_b32 v14, v39 offset:5292
	s_waitcnt vmcnt(1)
	ds_write_b32 v14, v40 offset:6336
	ds_write_b32 v14, v41 offset:6340
	ds_write_b32 v14, v42 offset:6344
	ds_write_b32 v14, v43 offset:6348
	s_waitcnt vmcnt(0)
	ds_write_b32 v14, v44 offset:7392
	ds_write_b32 v14, v45 offset:7396
	ds_write_b32 v14, v46 offset:7400
	ds_write_b32 v14, v47 offset:7404
	s_waitcnt lgkmcnt(0)
	ds_read2_b32 v[80:81], v15 offset0:0 offset1:33
	ds_read2_b32 v[82:83], v15 offset0:66 offset1:99
	ds_read2_b32 v[84:85], v15 offset0:132 offset1:165
	ds_read2_b32 v[86:87], v15 offset0:198 offset1:231
	ds_read2_b32 v[88:89], v15 offset0:8 offset1:41
	ds_read2_b32 v[90:91], v15 offset0:74 offset1:107
	ds_read2_b32 v[92:93], v15 offset0:140 offset1:173
	ds_read2_b32 v[94:95], v15 offset0:206 offset1:239
	s_waitcnt lgkmcnt(4)
	v_cvt_pk_bf16_f32 v112, v80, v81
	v_cvt_pk_bf16_f32 v113, v82, v83
	v_cvt_pk_bf16_f32 v114, v84, v85
	v_cvt_pk_bf16_f32 v115, v86, v87
	global_store_dwordx4 v4, v[112:115], s[16:17]
	s_waitcnt lgkmcnt(0)
	v_cvt_pk_bf16_f32 v116, v88, v89
	v_cvt_pk_bf16_f32 v117, v90, v91
	v_cvt_pk_bf16_f32 v118, v92, v93
	v_cvt_pk_bf16_f32 v119, v94, v95
	global_store_dwordx4 v5, v[116:119], s[16:17]
	ds_read2_b32 v[96:97], v15 offset0:16 offset1:49
	ds_read2_b32 v[98:99], v15 offset0:82 offset1:115
	ds_read2_b32 v[100:101], v15 offset0:148 offset1:181
	ds_read2_b32 v[102:103], v15 offset0:214 offset1:247
	ds_read2_b32 v[104:105], v15 offset0:24 offset1:57
	ds_read2_b32 v[106:107], v15 offset0:90 offset1:123
	ds_read2_b32 v[108:109], v15 offset0:156 offset1:189
	ds_read2_b32 v[110:111], v15 offset0:222 offset1:255
	s_waitcnt lgkmcnt(4)
	v_cvt_pk_bf16_f32 v120, v96, v97
	v_cvt_pk_bf16_f32 v121, v98, v99
	v_cvt_pk_bf16_f32 v122, v100, v101
	v_cvt_pk_bf16_f32 v123, v102, v103
	global_store_dwordx4 v6, v[120:123], s[16:17]
	s_waitcnt lgkmcnt(0)
	v_cvt_pk_bf16_f32 v124, v104, v105
	v_cvt_pk_bf16_f32 v125, v106, v107
	v_cvt_pk_bf16_f32 v126, v108, v109
	v_cvt_pk_bf16_f32 v127, v110, v111
	global_store_dwordx4 v7, v[124:127], s[16:17]
	s_addk_i32 s26, 0x400
	s_branch .Lffn2w_w4
.Lffn2w_done:
.LBB0_1819:
	s_cmpk_lt_u32 s28, 0x80
	s_cbranch_scc1 .LBB0_1869
	s_waitcnt vmcnt(0)
	v_readlane_b32 s0, v238, 0
	v_readlane_b32 s1, v238, 1
	s_waitcnt vmcnt(0) lgkmcnt(0)
	s_barrier
	s_and_saveexec_b64 s[2:3], s[0:1]
	s_cbranch_execz .LBB0_1827
	s_add_i32 s4, 0, 0x23528
	v_mov_b32_e32 v0, s4
	ds_read_b64 v[0:1], v0
	s_mov_b64 s[6:7], exec
	buffer_wbl2 sc1
	s_waitcnt lgkmcnt(0)
	s_waitcnt vmcnt(0)
	v_readfirstlane_b32 s4, v0
	v_mbcnt_lo_u32_b32 v0, s6, 0
	v_readfirstlane_b32 s5, v1
	s_add_u32 s4, s4, 0x3180200
	v_mbcnt_hi_u32_b32 v0, s7, v0
	s_addc_u32 s5, s5, 0
	v_cmp_eq_u32_e32 vcc, 0, v0
	s_and_saveexec_b64 s[8:9], vcc
	s_cbranch_execz .LBB0_1823
	s_bcnt1_i32_b64 s6, s[6:7]
	v_mov_b32_e32 v0, 0
	v_mov_b32_e32 v1, s6
	global_atomic_add v0, v1, s[4:5]
